# P0: gate-column table loads issued at phase start into spare registers, multiply/LDS write/barrier deferred to after the weight-transpose part (first weight items no longer wait for the table's round
# speedup vs baseline: 1.0093x; 1.0093x over previous
.LBB0_19:
	v_lshrrev_b32_e32 v12, 3, v128
	v_lshlrev_b32_e32 v13, 2, v12
	v_mad_u64_u32 v[14:15], s[0:1], v12, s19, v[6:7]
	v_lshl_add_u64 v[14:15], v[14:15], 0, v[2:3]
	s_mov_b64 s[98:99], 0x2000
	v_lshl_add_u64 v[14:15], v[14:15], 0, s[98:99]
	s_mov_b64 s[98:99], 0x100800
	v_add_u32_e32 v16, 0x11000, v1
	v_lshrrev_b32_e32 v17, 5, v128
	v_lshl_add_u32 v16, v17, 4, v16
	global_load_dword v140, v13, s[64:65]
	global_load_dword v156, v[14:15], off
	v_lshl_add_u64 v[14:15], v[14:15], 0, s[98:99]
	global_load_dword v141, v13, s[64:65] offset:256
	global_load_dword v157, v[14:15], off
	v_lshl_add_u64 v[14:15], v[14:15], 0, s[98:99]
	global_load_dword v142, v13, s[64:65] offset:512
	global_load_dword v158, v[14:15], off
	v_lshl_add_u64 v[14:15], v[14:15], 0, s[98:99]
	global_load_dword v143, v13, s[64:65] offset:768
	global_load_dword v159, v[14:15], off
	v_lshl_add_u64 v[14:15], v[14:15], 0, s[98:99]
	global_load_dword v144, v13, s[64:65] offset:1024
	global_load_dword v160, v[14:15], off
	v_lshl_add_u64 v[14:15], v[14:15], 0, s[98:99]
	global_load_dword v145, v13, s[64:65] offset:1280
	global_load_dword v161, v[14:15], off
	v_lshl_add_u64 v[14:15], v[14:15], 0, s[98:99]
	global_load_dword v146, v13, s[64:65] offset:1536
	global_load_dword v162, v[14:15], off
	v_lshl_add_u64 v[14:15], v[14:15], 0, s[98:99]
	global_load_dword v147, v13, s[64:65] offset:1792
	global_load_dword v163, v[14:15], off
	v_lshl_add_u64 v[14:15], v[14:15], 0, s[98:99]
	global_load_dword v148, v13, s[64:65] offset:2048
	global_load_dword v164, v[14:15], off
	v_lshl_add_u64 v[14:15], v[14:15], 0, s[98:99]
	global_load_dword v149, v13, s[64:65] offset:2304
	global_load_dword v165, v[14:15], off
	v_lshl_add_u64 v[14:15], v[14:15], 0, s[98:99]
	global_load_dword v150, v13, s[64:65] offset:2560
	global_load_dword v166, v[14:15], off
	v_lshl_add_u64 v[14:15], v[14:15], 0, s[98:99]
	global_load_dword v151, v13, s[64:65] offset:2816
	global_load_dword v167, v[14:15], off
	v_lshl_add_u64 v[14:15], v[14:15], 0, s[98:99]
	global_load_dword v152, v13, s[64:65] offset:3072
	global_load_dword v168, v[14:15], off
	v_lshl_add_u64 v[14:15], v[14:15], 0, s[98:99]
	global_load_dword v153, v13, s[64:65] offset:3328
	global_load_dword v169, v[14:15], off
	v_lshl_add_u64 v[14:15], v[14:15], 0, s[98:99]
	global_load_dword v154, v13, s[64:65] offset:3584
	global_load_dword v170, v[14:15], off
	v_lshl_add_u64 v[14:15], v[14:15], 0, s[98:99]
	global_load_dword v155, v13, s[64:65] offset:3840
	global_load_dword v171, v[14:15], off
	s_mov_b32 s18, 16
	v_mov_b32_e32 v172, v16
	s_or_b64 exec, exec, s[16:17]
	v_and_b32_e32 v3, 2, v10
	v_cmp_eq_u32_e32 vcc, 0, v3
	s_and_saveexec_b64 s[0:1], vcc
	s_cbranch_execz .LBB0_22
	v_lshrrev_b32_e32 v3, 3, v5
	v_lshrrev_b32_e32 v10, 3, v4
	s_movk_i32 s14, 0x4020
	v_mov_b64_e32 v[6:7], s[56:57]
	v_lshlrev_b32_e32 v4, 2, v10
	v_lshlrev_b32_e32 v5, 2, v3
	v_mad_u64_u32 v[10:11], s[16:17], v10, s14, v[6:7]
	v_mad_u64_u32 v[6:7], s[16:17], v3, s14, v[6:7]
	v_mov_b32_e32 v3, 0
	v_lshl_add_u64 v[10:11], v[10:11], 0, v[2:3]
	s_movk_i32 s14, 0x2000
	v_lshl_add_u64 v[2:3], v[6:7], 0, v[2:3]
	v_add_co_u32_e32 v6, vcc, s14, v10
	global_load_dword v4, v4, s[64:65]
	s_nop 0
	global_load_dword v5, v5, s[64:65]
	v_addc_co_u32_e32 v7, vcc, 0, v11, vcc
	v_add_co_u32_e32 v2, vcc, s14, v2
	s_nop 1
	v_addc_co_u32_e32 v3, vcc, 0, v3, vcc
	global_load_dword v6, v[6:7], off
	s_nop 0
	global_load_dword v7, v[2:3], off
	v_lshl_or_b32 v2, v9, 11, v1
	v_add_u32_e32 v9, 0, v2
	s_waitcnt vmcnt(0)
	v_pk_mul_f32 v[2:3], v[4:5], v[6:7]
	v_add_u32_e32 v4, 0x11000, v9
	ds_write2st64_b32 v4, v2, v3 offset1:8

.LBB0_145:
	s_or_b64 exec, exec, s[16:17]
	v_mul_f32_e32 v140, v140, v156
	v_mul_f32_e32 v141, v141, v157
	v_mul_f32_e32 v142, v142, v158
	v_mul_f32_e32 v143, v143, v159
	v_mul_f32_e32 v144, v144, v160
	v_mul_f32_e32 v145, v145, v161
	v_mul_f32_e32 v146, v146, v162
	v_mul_f32_e32 v147, v147, v163
	v_mul_f32_e32 v148, v148, v164
	v_mul_f32_e32 v149, v149, v165
	v_mul_f32_e32 v150, v150, v166
	v_mul_f32_e32 v151, v151, v167
	v_mul_f32_e32 v152, v152, v168
	v_mul_f32_e32 v153, v153, v169
	v_mul_f32_e32 v154, v154, v170
	v_mul_f32_e32 v155, v155, v171
	ds_write_b32 v172, v140
	ds_write_b32 v172, v141 offset:2304
	ds_write_b32 v172, v142 offset:4608
	ds_write_b32 v172, v143 offset:6912
	ds_write_b32 v172, v144 offset:9216
	ds_write_b32 v172, v145 offset:11520
	ds_write_b32 v172, v146 offset:13824
	ds_write_b32 v172, v147 offset:16128
	ds_write_b32 v172, v148 offset:18432
	ds_write_b32 v172, v149 offset:20736
	ds_write_b32 v172, v150 offset:23040
	ds_write_b32 v172, v151 offset:25344
	ds_write_b32 v172, v152 offset:27648
	ds_write_b32 v172, v153 offset:29952
	ds_write_b32 v172, v154 offset:32256
	ds_write_b32 v172, v155 offset:34560
	s_waitcnt lgkmcnt(0)
	s_barrier
	s_movk_i32 s0, 0xe80
	v_cmp_gt_i32_e32 vcc, s0, v81
	s_and_saveexec_b64 s[0:1], vcc
	v_readlane_b32 s96, v255, 40
	v_readlane_b32 s94, v255, 37
	v_readlane_b32 s82, v255, 35
	v_readlane_b32 s97, v255, 41
	v_readlane_b32 s93, v255, 39
	v_readlane_b32 s95, v255, 38
	v_readlane_b32 s83, v255, 36
	s_cbranch_execz .LBB0_226
	v_mbcnt_lo_u32_b32 v0, -1, 0
	v_mbcnt_hi_u32_b32 v0, -1, v0
	v_and_b32_e32 v1, 64, v0
	v_add_u32_e32 v1, 64, v1
	v_xor_b32_e32 v2, 1, v0
	v_cmp_lt_i32_e32 vcc, v2, v1
	s_add_u32 s56, s28, 0x2300000
	s_addc_u32 s57, s29, 0
	v_cndmask_b32_e32 v2, v0, v2, vcc
	v_lshlrev_b32_e32 v111, 2, v2
	v_xor_b32_e32 v2, 2, v0
	v_cmp_lt_i32_e32 vcc, v2, v1
	s_add_u32 s64, s28, 0x3000000
	s_addc_u32 s65, s29, 0
	v_cndmask_b32_e32 v2, v0, v2, vcc
	v_lshlrev_b32_e32 v112, 2, v2
	v_xor_b32_e32 v2, 4, v0
	v_cmp_lt_i32_e32 vcc, v2, v1
	s_add_i32 s4, 0, 0x11000
	v_lshl_add_u32 v110, v80, 7, s4
	v_lshl_add_u32 v110, v80, 4, v110
	v_cndmask_b32_e32 v2, v0, v2, vcc
	v_lshlrev_b32_e32 v113, 2, v2
	v_xor_b32_e32 v2, 8, v0
	v_cmp_lt_i32_e32 vcc, v2, v1
	s_mul_i32 s4, s22, 40
	s_waitcnt vmcnt(7)
	v_mov_b32_e32 v83, 0
	v_cndmask_b32_e32 v2, v0, v2, vcc
	v_lshlrev_b32_e32 v114, 2, v2
	v_xor_b32_e32 v2, 16, v0
	v_cmp_lt_i32_e32 vcc, v2, v1
	s_waitcnt vmcnt(6)
	v_lshlrev_b32_e32 v84, 4, v80
	v_cmp_eq_u32_e64 s[2:3], 0, v80
	v_cndmask_b32_e32 v2, v0, v2, vcc
	v_lshlrev_b32_e32 v115, 2, v2
	v_xor_b32_e32 v2, 32, v0
	v_cmp_lt_i32_e32 vcc, v2, v1
	s_mul_i32 s68, s34, 40
	s_mov_b64 s[16:17], 0
	v_cndmask_b32_e32 v0, v0, v2, vcc
	v_lshlrev_b32_e32 v116, 2, v0
	v_mad_u32_u24 v0, v58, 5, s4
	v_add_u32_e32 v82, 0xffffbf80, v0
	s_movk_i32 s69, 0xce6
	s_movk_i32 s71, 0xce7
	s_movk_i32 s72, 0xccc
	v_mov_b32_e32 v86, v84
	v_mov_b32_e32 v87, v83
	s_movk_i32 s73, 0xce5
	s_movk_i32 s74, 0xccb
	s_movk_i32 s75, 0x7fff
	v_mov_b32_e32 v117, 0x358637bd
	s_mov_b32 s76, 0x800000
	s_mov_b32 s77, 0x43000
	s_movk_i32 s78, 0xe7f
	v_mov_b32_e32 v118, 1
	s_branch .LBB0_149
